# v17final
# speedup vs baseline: 1.0535x; 1.0007x over previous
; DEVINL int v_st(int k, int c) { const int kk = (k & ~0xC) | ((k & 4) << 1) | ((k & 8) >> 1); return ((kk >> 3) * 4 + (c >> 5)) * 512 + ((kk & 7) * 32 + (c & 31)) * 2; }
; DEVINL int v_rd_base(int lane) { return ((lane & 3) << 3) | (((lane >> 2) & 3) << 6) | (((lane >> 4) & 1) << 5) | (((lane >> 5) & 1) << 8); }
; template <bool DIFF>
; DEVINL bool attn_is_fast(const bf16* __restrict__ Qb, int ldq, float kmax, char* lds) {
;     ...
;   if (lane == 0) red[wid] = qs;
;   __syncthreads();
;   float qm = red[0];
; #pragma unroll
;   for (int w = 1; w < 8; ++w) qm = fmaxf(qm, red[w]);
;   __syncthreads();
;   const int f = (sqrtf(qm) * kmax < 100.f) ? 1 : 0;
;   return __builtin_amdgcn_readfirstlane(f) != 0;
; template <bool DIFF, bool FAST> ...
;     ...
;   float m_reg = -1e30f, l_reg = 0; f32x16 o[4] = {}; bf16x8 qr[ND0];
;   const bf16* Qw = Qb + (size_t)(rg * 32 + r32) * ldq + comp * 64 + hi * 8;
; #pragma unroll
;   for (int d0 = 0; d0 < ND0; ++d0) qr[d0] = *reinterpret_cast<const bf16x8*>(Qw + d0 * 16);
;   const int colbase = comp * 64;
;   const int sr = tid >> 4, sc = (tid & 15) * 8, vst0 = v_st(sr, sc), vst1 = v_st(32 + sr, sc);
;   const int vb0 = (int)(uintptr_t)V_lds + v_rd_base(lane);
;   struct { bf16x8 vs0, vs1, ks0, ks1; } sr_[2];
.LBB0_533:
	s_or_b64 exec, exec, s[8:9]
	v_mov_b32_e32 v0, 0x10800
	s_lshl_b64 s[8:9], s[12:13], 9
	v_readlane_b32 s18, v254, 61
	s_waitcnt lgkmcnt(0)
	s_barrier
	ds_read_b128 v[0:3], v0
	v_readlane_b32 s19, v254, 62
	s_add_u32 s18, s18, s8
	s_addc_u32 s19, s19, s9
	s_lshl_b32 s10, s10, 5
	s_and_b32 s10, s10, 0xffffff80
	s_ashr_i32 s11, s10, 31
	s_lshl_b64 s[10:11], s[10:11], 1
	s_waitcnt lgkmcnt(0)
	v_max_f32_e32 v1, v1, v1
	v_max_f32_e32 v0, v0, v0
	s_add_u32 s28, s18, s10
	v_max_f32_e32 v0, v0, v1
	s_addc_u32 s29, s19, s11
	v_readlane_b32 s18, v254, 59
	v_max3_f32 v4, v0, v2, v3
	v_mov_b32_e32 v0, 0x10810
	v_readlane_b32 s19, v254, 60
	s_add_u32 s8, s18, s8
	ds_read_b128 v[0:3], v0
	s_addc_u32 s9, s19, s9
	s_add_u32 s10, s8, s10
	s_addc_u32 s11, s9, s11
	s_add_u32 s8, s66, s34
	s_addc_u32 s9, s67, s45
	s_waitcnt lgkmcnt(0)
	v_max3_f32 v0, v4, v0, v1
	s_add_u32 s8, s8, s6
	v_max3_f32 v0, v0, v2, v3
	s_addc_u32 s9, s9, s7
	v_cmp_gt_f32_e32 vcc, s75, v0
	v_mul_f32_e32 v1, 0x4f800000, v0
	s_add_u32 s20, s8, 0x1000
	v_cndmask_b32_e32 v0, v0, v1, vcc
	s_addc_u32 s21, s9, 0
	v_sqrt_f32_e32 v1, v0
	s_add_u32 s8, s96, s34
	s_addc_u32 s9, s97, s45
	s_add_u32 s6, s8, s6
	s_addc_u32 s7, s9, s7
	v_add_u32_e32 v2, -1, v1
	s_add_u32 s18, s6, 0x1000
	v_fma_f32 v3, -v2, v1, v0
	s_addc_u32 s19, s7, 0
	v_cmp_ge_f32_e64 s[6:7], 0, v3
	v_add_u32_e32 v3, 1, v1
	s_nop 0
	v_cndmask_b32_e64 v2, v1, v2, s[6:7]
	v_fma_f32 v1, -v3, v1, v0
	v_cmp_lt_f32_e64 s[6:7], 0, v1
	s_barrier
	s_nop 0
	v_cndmask_b32_e64 v1, v2, v3, s[6:7]
	v_mul_f32_e32 v2, 0x37800000, v1
	v_cndmask_b32_e32 v1, v1, v2, vcc
	v_cmp_class_f32_e32 vcc, v0, v246
	s_nop 1
	v_cndmask_b32_e32 v0, v1, v0, vcc
	v_mul_f32_e32 v0, v210, v0
	v_cmp_gt_f32_e32 vcc, s76, v0
	s_nop 1
	v_cndmask_b32_e64 v0, 0, 1, vcc
	s_nop 0
	v_readfirstlane_b32 s6, v0
	s_bitcmp0_b32 s6, 0
	s_mov_b64 s[6:7], -1
	s_cbranch_scc0 .LBB0_559
	s_movk_i32 s24, 0x100
	s_movk_i32 s6, 0x400
	s_mov_b32 s8, s44
	v_mov_b32_e32 v49, v186
	v_mov_b32_e32 v183, v113
	v_ashrrev_i32_e32 v185, 6, v49
	v_and_b32_e32 v190, 31, v49
	v_lshlrev_b32_e32 v184, 5, v185
	v_or_b32_e32 v0, v184, v190
	v_bfe_u32 v191, v49, 5, 1
	v_mad_i64_i32 v[0:1], s[6:7], v0, s6, 0
	v_lshl_add_u64 v[0:1], v[0:1], 1, s[36:37]
	v_lshlrev_b32_e32 v182, 4, v191
	v_lshl_add_u64 v[0:1], v[0:1], 0, v[182:183]
	v_ashrrev_i32_e32 v48, 4, v49
	global_load_dwordx4 v[142:145], v[0:1], off
	global_load_dwordx4 v[138:141], v[0:1], off offset:32
	global_load_dwordx4 v[134:137], v[0:1], off offset:64
	global_load_dwordx4 v[130:133], v[0:1], off offset:96
	global_load_dwordx4 v[126:129], v[0:1], off offset:128
	global_load_dwordx4 v[122:125], v[0:1], off offset:160
	global_load_dwordx4 v[118:121], v[0:1], off offset:192
	global_load_dwordx4 v[114:117], v[0:1], off offset:224
	v_and_b32_e32 v1, 0xfffff0, v48
	v_lshlrev_b32_e32 v2, 1, v48
	v_lshlrev_b32_e32 v0, 3, v49
	v_and_or_b32 v1, v2, 8, v1
	v_and_b32_e32 v112, 0x78, v0
	v_lshrrev_b32_e32 v2, 1, v48
	v_lshrrev_b32_e32 v1, 1, v1
	v_bfe_u32 v0, v0, 5, 2
	v_and_b32_e32 v3, 3, v48
	v_or_b32_e32 v1, v1, v0
	v_and_or_b32 v2, v2, 4, v3
	v_lshlrev_b32_e32 v6, 1, v112
	v_lshlrev_b32_e32 v1, 9, v1
	v_lshlrev_b32_e32 v2, 6, v2
	v_and_b32_e32 v3, 48, v6
	v_add_u32_e32 v7, 32, v48
	v_or3_b32 v214, v1, v2, v3
	v_and_b32_e32 v1, 0xfffff0, v7
	v_lshlrev_b32_e32 v4, 1, v7
	v_and_or_b32 v1, v4, 8, v1
	v_lshrrev_b32_e32 v1, 1, v1
	v_or_b32_e32 v0, v1, v0
	v_lshlrev_b32_e32 v0, 9, v0
	v_or3_b32 v219, v0, v2, v3
	v_mad_i64_i32 v[0:1], s[6:7], v48, s24, v[112:113]
	v_lshlrev_b64 v[0:1], 1, v[0:1]
	v_lshl_add_u64 v[2:3], s[10:11], 0, v[0:1]
	global_load_dwordx4 v[146:149], v[2:3], off
	v_mad_i64_i32 v[2:3], s[6:7], v7, s24, v[112:113]
	v_lshlrev_b64 v[2:3], 1, v[2:3]
	v_lshl_add_u64 v[4:5], s[10:11], 0, v[2:3]
	v_lshl_add_u64 v[0:1], s[28:29], 0, v[0:1]
	global_load_dwordx4 v[150:153], v[4:5], off
	global_load_dwordx4 v[154:157], v[0:1], off
	v_lshl_add_u64 v[0:1], s[28:29], 0, v[2:3]
	global_load_dwordx4 v[158:161], v[0:1], off
	v_lshlrev_b32_e32 v0, 8, v48
	v_and_b32_e32 v1, 0x70, v49
	v_bitop3_b32 v220, v6, v0, v1 bitop3:0xde
	v_lshlrev_b32_e32 v0, 8, v7
	v_bitop3_b32 v221, v6, v0, v1 bitop3:0xde
	v_lshlrev_b32_e32 v0, 4, v49
	v_lshlrev_b32_e32 v40, 8, v190
	v_and_b32_e32 v41, 0x70, v0
	v_bitop3_b32 v196, v182, v40, v41 bitop3:0xde
	s_waitcnt vmcnt(0)
	v_or_b32_e32 v32, 32, v182
	v_bitop3_b32 v197, v32, v40, v41 bitop3:0xde
	s_waitcnt vmcnt(3)
	ds_write_b128 v214, v[146:149]
	s_waitcnt vmcnt(2)
	ds_write_b128 v219, v[150:153]
	s_waitcnt vmcnt(1)
	ds_write_b128 v220, v[154:157] offset:32768
	s_waitcnt vmcnt(0)
	ds_write_b128 v221, v[158:161] offset:32768
	s_waitcnt lgkmcnt(0)
	s_barrier
; template <bool FAST>
; DEVINL void partialSM(f32x16& p0, f32x16& p1, float& m_reg, float& mn, float& alpha) {
;     ...
;     constexpr float THR2 = ATT_THR * 1.4426950408889634f;
;     float pmax = p0[0];
; #pragma unroll
;     for (int r = 1; r < 16; ++r) pmax = fmaxf(pmax, p0[r]);
; #pragma unroll
;     for (int r = 0; r < 16; ++r) pmax = fmaxf(pmax, p1[r]);
;     { auto rr = __builtin_amdgcn_permlane32_swap(__float_as_uint(pmax), __float_as_uint(pmax), false, false);
;       pmax = fmaxf(__uint_as_float(rr[0]), __uint_as_float(rr[1])); }
;     if (__builtin_expect(__all(pmax - m_reg <= THR2), 1)) { mn = m_reg; alpha = 1.f; }
;     else { mn = fmaxf(m_reg, pmax); alpha = __builtin_amdgcn_exp2f(m_reg - mn); m_reg = mn; }
; template <int ND0>
; DEVINL void qkt(f32x16& p0, f32x16& p1, const bf16* Ks, const bf16x8* qr, int r32, int hi, int colbase) {
;   p0 = f32x16{}; p1 = f32x16{};
;   __builtin_amdgcn_iglp_opt(1);
; #pragma unroll
;   for (int d0 = 0; d0 < ND0; ++d0) { int cb = (colbase + d0 * 16 + hi * 8) * 2;
;     bf16x8 b0 = *reinterpret_cast<const bf16x8*>((const char*)Ks + KSWZ(r32, cb));
;     bf16x8 b1 = *reinterpret_cast<const bf16x8*>((const char*)Ks + KSWZ(32 + r32, cb));
;     p0 = __builtin_amdgcn_mfma_f32_32x32x16_bf16(b0, qr[d0], p0, 0, 0, 0);
;     p1 = __builtin_amdgcn_mfma_f32_32x32x16_bf16(b1, qr[d0], p1, 0, 0, 0); }
; }
	ds_read_b128 v[0:3], v196 offset:32768
	ds_read_b128 v[32:35], v197 offset:32768
	ds_read_b128 v[4:7], v196 offset:40960
	ds_read_b128 v[36:39], v197 offset:40960
	s_waitcnt lgkmcnt(3)
	v_mfma_f32_32x32x16_bf16 v[16:31], v[0:3], v[142:145], 0
	s_waitcnt lgkmcnt(2)
	v_mfma_f32_32x32x16_bf16 v[16:31], v[32:35], v[138:141], v[16:31]
	v_or_b32_e32 v32, 64, v182
	v_bitop3_b32 v212, v32, v40, v41 bitop3:0xde
	ds_read_b128 v[32:35], v212 offset:32768
	s_waitcnt lgkmcnt(2)
	v_mfma_f32_32x32x16_bf16 v[0:15], v[4:7], v[142:145], 0
	s_waitcnt lgkmcnt(1)
	v_mfma_f32_32x32x16_bf16 v[0:15], v[36:39], v[138:141], v[0:15]
	ds_read_b128 v[36:39], v212 offset:40960
	s_waitcnt lgkmcnt(1)
	v_mfma_f32_32x32x16_bf16 v[16:31], v[32:35], v[134:137], v[16:31]
	v_or_b32_e32 v32, 0x60, v182
	v_bitop3_b32 v218, v32, v40, v41 bitop3:0xde
	ds_read_b128 v[32:35], v218 offset:32768
	s_waitcnt lgkmcnt(1)
	v_mfma_f32_32x32x16_bf16 v[0:15], v[36:39], v[134:137], v[0:15]
	ds_read_b128 v[36:39], v218 offset:40960
	s_waitcnt lgkmcnt(1)
	v_mfma_f32_32x32x16_bf16 v[16:31], v[32:35], v[130:133], v[16:31]
	v_or_b32_e32 v32, 0x80, v182
	v_bitop3_b32 v216, v32, v40, v41 bitop3:0xde
	ds_read_b128 v[32:35], v216 offset:32768
	s_waitcnt lgkmcnt(1)
	v_mfma_f32_32x32x16_bf16 v[0:15], v[36:39], v[130:133], v[0:15]
	ds_read_b128 v[36:39], v216 offset:40960
	s_waitcnt lgkmcnt(1)
	v_mfma_f32_32x32x16_bf16 v[16:31], v[32:35], v[126:129], v[16:31]
	v_or_b32_e32 v32, 0xa0, v182
	v_bitop3_b32 v215, v32, v40, v41 bitop3:0xde
	ds_read_b128 v[32:35], v215 offset:32768
	s_waitcnt lgkmcnt(1)
	v_mfma_f32_32x32x16_bf16 v[0:15], v[36:39], v[126:129], v[0:15]
	ds_read_b128 v[36:39], v215 offset:40960
	s_waitcnt lgkmcnt(1)
	v_mfma_f32_32x32x16_bf16 v[16:31], v[32:35], v[122:125], v[16:31]
	v_or_b32_e32 v32, 0xc0, v182
	v_bitop3_b32 v213, v32, v40, v41 bitop3:0xde
	ds_read_b128 v[32:35], v213 offset:32768
	s_waitcnt lgkmcnt(1)
	v_mfma_f32_32x32x16_bf16 v[0:15], v[36:39], v[122:125], v[0:15]
	ds_read_b128 v[36:39], v213 offset:40960
	s_waitcnt lgkmcnt(1)
	v_mfma_f32_32x32x16_bf16 v[16:31], v[32:35], v[118:121], v[16:31]
	v_or_b32_e32 v32, 0xe0, v182
	v_bitop3_b32 v217, v32, v40, v41 bitop3:0xde
	ds_read_b128 v[32:35], v217 offset:32768
	s_waitcnt lgkmcnt(1)
	v_mfma_f32_32x32x16_bf16 v[0:15], v[36:39], v[118:121], v[0:15]
	ds_read_b128 v[36:39], v217 offset:40960
	s_waitcnt lgkmcnt(0)
	v_mfma_f32_32x32x16_bf16 v[0:15], v[36:39], v[114:117], v[0:15]
	v_add_u32_e32 v36, 0x60, v48
	v_mad_i64_i32 v[36:37], s[6:7], v36, s24, v[112:113]
	v_lshlrev_b64 v[44:45], 1, v[36:37]
	v_lshl_add_u64 v[36:37], s[10:11], 0, v[44:45]
	v_lshl_add_u64 v[44:45], s[28:29], 0, v[44:45]
	v_mfma_f32_32x32x16_bf16 v[16:31], v[32:35], v[114:117], v[16:31]
	global_load_dwordx4 v[44:47], v[44:45], off
	s_nop 10
	v_max_f32_e32 v32, v17, v17
	v_max_f32_e32 v33, v16, v16
	v_max_f32_e32 v32, v33, v32
	v_max3_f32 v32, v32, v18, v19
	v_max3_f32 v32, v32, v20, v21
	v_max3_f32 v32, v32, v22, v23
	v_max3_f32 v32, v32, v24, v25
	v_max3_f32 v32, v32, v26, v27
	v_max3_f32 v32, v32, v28, v29
	v_max3_f32 v32, v32, v30, v31
	v_max3_f32 v32, v32, v0, v1
	v_max3_f32 v32, v32, v2, v3
	v_max3_f32 v32, v32, v4, v5
	v_max3_f32 v32, v32, v6, v7
	v_max3_f32 v32, v32, v8, v9
	v_max3_f32 v32, v32, v10, v11
	v_max3_f32 v32, v32, v12, v13
	v_max3_f32 v32, v32, v14, v15
	v_mov_b32_e32 v33, v32
	s_nop 1
	v_permlane32_swap_b32_e32 v32, v33
	v_max_f32_e32 v33, v33, v33
	v_max_f32_e32 v32, v32, v32
	v_max_f32_e32 v50, v32, v33
	v_add_f32_e32 v32, 0x7149f2ca, v50
	v_cmp_ge_f32_e32 vcc, s78, v32
	v_add_u32_e32 v32, 64, v48
	v_mad_i64_i32 v[32:33], s[6:7], v32, s24, v[112:113]
	v_lshlrev_b64 v[40:41], 1, v[32:33]
	v_lshl_add_u64 v[32:33], s[10:11], 0, v[40:41]
	v_lshl_add_u64 v[40:41], s[28:29], 0, v[40:41]
	global_load_dwordx4 v[40:43], v[40:41], off
	s_cmp_eq_u64 vcc, exec
	global_load_dwordx4 v[36:39], v[36:37], off
	s_cselect_b64 vcc, -1, 0
	global_load_dwordx4 v[32:35], v[32:33], off
	s_cmpk_gt_i32 s8, 0xbf
	s_cselect_b64 s[6:7], -1, 0
	s_cmpk_lt_i32 s8, 0xc0
	s_cbranch_scc1 .LBB0_536
	v_add_u32_e32 v51, 0x80, v48
	v_mad_i64_i32 v[52:53], s[26:27], v51, s24, v[112:113]
	v_add_u32_e32 v51, 0xa0, v48
	v_lshlrev_b64 v[52:53], 1, v[52:53]
	v_mad_i64_i32 v[56:57], s[26:27], v51, s24, v[112:113]
	v_lshl_add_u64 v[54:55], s[10:11], 0, v[52:53]
	v_lshlrev_b64 v[56:57], 1, v[56:57]
	v_lshl_add_u64 v[52:53], s[28:29], 0, v[52:53]
	v_lshl_add_u64 v[58:59], s[10:11], 0, v[56:57]
	global_load_dwordx4 v[146:149], v[54:55], off
	global_load_dwordx4 v[150:153], v[58:59], off
	v_lshl_add_u64 v[54:55], s[28:29], 0, v[56:57]
	global_load_dwordx4 v[154:157], v[52:53], off
	global_load_dwordx4 v[158:161], v[54:55], off

; DEVINL int v_st(int k, int c) { const int kk = (k & ~0xC) | ((k & 4) << 1) | ((k & 8) >> 1); return ((kk >> 3) * 4 + (c >> 5)) * 512 + ((kk & 7) * 32 + (c & 31)) * 2; }
; DEVINL int v_rd_base(int lane) { return ((lane & 3) << 3) | (((lane >> 2) & 3) << 6) | (((lane >> 4) & 1) << 5) | (((lane >> 5) & 1) << 8); }
; template <bool DIFF>
; DEVINL bool attn_is_fast(const bf16* __restrict__ Qb, int ldq, float kmax, char* lds) {
;     ...
;   if (lane == 0) red[wid] = qs;
;   __syncthreads();
;   float qm = red[0];
; #pragma unroll
;   for (int w = 1; w < 8; ++w) qm = fmaxf(qm, red[w]);
;   __syncthreads();
;   const int f = (sqrtf(qm) * kmax < 100.f) ? 1 : 0;
;   return __builtin_amdgcn_readfirstlane(f) != 0;
; template <bool DIFF, bool FAST> ...
;     ...
;   float m_reg = -1e30f, l_reg = 0; f32x16 o[4] = {}; bf16x8 qr[ND0];
;   const bf16* Qw = Qb + (size_t)(rg * 32 + r32) * ldq + comp * 64 + hi * 8;
; #pragma unroll
;   for (int d0 = 0; d0 < ND0; ++d0) qr[d0] = *reinterpret_cast<const bf16x8*>(Qw + d0 * 16);
;   const int colbase = comp * 64;
;   const int sr = tid >> 4, sc = (tid & 15) * 8, vst0 = v_st(sr, sc), vst1 = v_st(32 + sr, sc);
;   const int vb0 = (int)(uintptr_t)V_lds + v_rd_base(lane);
;   struct { bf16x8 vs0, vs1, ks0, ks1; } sr_[2];
.LBB0_573:
	s_or_b64 exec, exec, s[8:9]
	v_mov_b32_e32 v0, 0x10800
	s_waitcnt lgkmcnt(0)
	s_barrier
	ds_read_b128 v[0:3], v0
	s_lshl_b64 s[8:9], s[12:13], 11
	v_readlane_b32 s12, v255, 3
	v_readlane_b32 s13, v255, 4
	s_add_u32 s12, s12, s8
	s_waitcnt lgkmcnt(0)
	v_max_f32_e32 v1, v1, v1
	v_max_f32_e32 v0, v0, v0
	v_max_f32_e32 v0, v0, v1
	v_max3_f32 v4, v0, v2, v3
	v_mov_b32_e32 v0, 0x10810
	ds_read_b128 v[0:3], v0
	s_addc_u32 s13, s13, s9
	s_add_u32 s16, s12, s6
	s_addc_u32 s17, s13, s7
	v_readlane_b32 s12, v255, 1
	v_readlane_b32 s13, v255, 2
	s_add_u32 s8, s12, s8
	s_addc_u32 s9, s13, s9
	s_waitcnt lgkmcnt(0)
	v_max3_f32 v0, v4, v0, v1
	s_add_u32 s18, s8, s6
	v_max3_f32 v0, v0, v2, v3
	s_addc_u32 s19, s9, s7
	v_cmp_gt_f32_e32 vcc, s75, v0
	v_mul_f32_e32 v1, 0x4f800000, v0
	s_add_u32 s8, s66, s34
	v_cndmask_b32_e32 v0, v0, v1, vcc
	s_addc_u32 s9, s67, s45
	v_sqrt_f32_e32 v1, v0
	s_add_u32 s14, s8, s6
	s_addc_u32 s15, s9, s7
	s_add_u32 s8, s96, s34
	s_addc_u32 s9, s97, s45
	v_add_u32_e32 v2, -1, v1
	s_add_u32 s12, s8, s6
	v_fma_f32 v3, -v2, v1, v0
	s_addc_u32 s13, s9, s7
	v_cmp_ge_f32_e64 s[6:7], 0, v3
	v_add_u32_e32 v3, 1, v1
	s_nop 0
	v_cndmask_b32_e64 v2, v1, v2, s[6:7]
	v_fma_f32 v1, -v3, v1, v0
	v_cmp_lt_f32_e64 s[6:7], 0, v1
	s_barrier
	s_nop 0
	v_cndmask_b32_e64 v1, v2, v3, s[6:7]
	v_mul_f32_e32 v2, 0x37800000, v1
	v_cndmask_b32_e32 v1, v1, v2, vcc
	v_cmp_class_f32_e32 vcc, v0, v246
	s_nop 1
	v_cndmask_b32_e32 v0, v1, v0, vcc
	v_mul_f32_e32 v0, v209, v0
	v_cmp_gt_f32_e32 vcc, s76, v0
	s_nop 1
	v_cndmask_b32_e64 v0, 0, 1, vcc
	s_nop 0
	v_readfirstlane_b32 s6, v0
	s_bitcmp0_b32 s6, 0
	s_mov_b64 s[6:7], -1
	s_cbranch_scc0 .LBB0_602
	s_mov_b32 s8, s44
	s_movk_i32 s6, 0x400
	s_movk_i32 s24, 0x400
	v_mov_b32_e32 v167, v186
	v_mov_b32_e32 v163, v113
	v_lshrrev_b32_e32 v0, 1, v167
	v_and_b32_e32 v164, 31, v167
	v_and_b32_e32 v166, 0x60, v0
	v_ashrrev_i32_e32 v168, 8, v167
	v_or_b32_e32 v0, v166, v164
	v_mad_i64_i32 v[0:1], s[6:7], v0, s6, 0
	v_lshlrev_b32_e32 v2, 6, v168
	v_bfe_u32 v165, v167, 5, 1
	v_lshl_add_u64 v[0:1], v[0:1], 1, s[10:11]
	v_ashrrev_i32_e32 v3, 31, v2
	v_lshl_add_u64 v[0:1], v[2:3], 1, v[0:1]
	v_lshlrev_b32_e32 v162, 4, v165
	v_lshl_add_u64 v[0:1], v[0:1], 0, v[162:163]
	v_ashrrev_i32_e32 v48, 4, v167
	global_load_dwordx4 v[126:129], v[0:1], off
	global_load_dwordx4 v[122:125], v[0:1], off offset:32
	global_load_dwordx4 v[118:121], v[0:1], off offset:64
	global_load_dwordx4 v[114:117], v[0:1], off offset:96
	v_and_b32_e32 v1, 0xfffff0, v48
	v_lshlrev_b32_e32 v2, 1, v48
	v_lshlrev_b32_e32 v0, 3, v167
	v_and_or_b32 v1, v2, 8, v1
	v_and_b32_e32 v112, 0x78, v0
	v_lshrrev_b32_e32 v2, 1, v48
	v_lshrrev_b32_e32 v1, 1, v1
	v_bfe_u32 v0, v0, 5, 2
	v_and_b32_e32 v3, 3, v48
	v_or_b32_e32 v1, v1, v0
	v_and_or_b32 v2, v2, 4, v3
	v_lshlrev_b32_e32 v6, 1, v112
	v_lshlrev_b32_e32 v1, 9, v1
	v_lshlrev_b32_e32 v2, 6, v2
	v_and_b32_e32 v3, 48, v6
	v_add_u32_e32 v7, 32, v48
	v_or3_b32 v176, v1, v2, v3
	v_and_b32_e32 v1, 0xfffff0, v7
	v_lshlrev_b32_e32 v4, 1, v7
	v_and_or_b32 v1, v4, 8, v1
	v_lshrrev_b32_e32 v1, 1, v1
	v_or_b32_e32 v0, v1, v0
	v_lshlrev_b32_e32 v0, 9, v0
	v_or3_b32 v178, v0, v2, v3
	v_mad_i64_i32 v[0:1], s[6:7], v48, s24, v[112:113]
	v_lshlrev_b64 v[0:1], 1, v[0:1]
	v_lshl_add_u64 v[2:3], s[18:19], 0, v[0:1]
	global_load_dwordx4 v[130:133], v[2:3], off
	v_mad_i64_i32 v[2:3], s[6:7], v7, s24, v[112:113]
	v_lshlrev_b64 v[2:3], 1, v[2:3]
	v_lshl_add_u64 v[4:5], s[18:19], 0, v[2:3]
	v_lshl_add_u64 v[0:1], s[16:17], 0, v[0:1]
	global_load_dwordx4 v[134:137], v[4:5], off
	global_load_dwordx4 v[138:141], v[0:1], off
	v_lshl_add_u64 v[0:1], s[16:17], 0, v[2:3]
	global_load_dwordx4 v[142:145], v[0:1], off
	v_lshlrev_b32_e32 v0, 8, v48
	v_and_b32_e32 v1, 0x70, v167
	v_bitop3_b32 v179, v6, v0, v1 bitop3:0xde
	v_lshlrev_b32_e32 v0, 8, v7
	v_bitop3_b32 v180, v6, v0, v1 bitop3:0xde
	v_lshlrev_b32_e32 v0, 4, v167
	v_lshl_or_b32 v40, v168, 7, v162
	v_lshlrev_b32_e32 v41, 8, v164
	v_and_b32_e32 v42, 0x70, v0
	v_xad_u32 v173, v40, v42, v41
	s_waitcnt vmcnt(0)
	v_or_b32_e32 v32, 32, v40
	v_xad_u32 v174, v32, v42, v41
	s_waitcnt vmcnt(3)
	ds_write_b128 v176, v[130:133]
	s_waitcnt vmcnt(2)
	ds_write_b128 v178, v[134:137]
	s_waitcnt vmcnt(1)
	ds_write_b128 v179, v[138:141] offset:32768
	s_waitcnt vmcnt(0)
	ds_write_b128 v180, v[142:145] offset:32768
	s_waitcnt lgkmcnt(0)
	s_barrier
; template <bool FAST>
; DEVINL void partialSM(f32x16& p0, f32x16& p1, float& m_reg, float& mn, float& alpha) {
;     ...
;     constexpr float THR2 = ATT_THR * 1.4426950408889634f;
;     float pmax = p0[0];
; #pragma unroll
;     for (int r = 1; r < 16; ++r) pmax = fmaxf(pmax, p0[r]);
; #pragma unroll
;     for (int r = 0; r < 16; ++r) pmax = fmaxf(pmax, p1[r]);
;     { auto rr = __builtin_amdgcn_permlane32_swap(__float_as_uint(pmax), __float_as_uint(pmax), false, false);
;       pmax = fmaxf(__uint_as_float(rr[0]), __uint_as_float(rr[1])); }
;     if (__builtin_expect(__all(pmax - m_reg <= THR2), 1)) { mn = m_reg; alpha = 1.f; }
;     else { mn = fmaxf(m_reg, pmax); alpha = __builtin_amdgcn_exp2f(m_reg - mn); m_reg = mn; }
; template <int ND0>
; DEVINL void qkt(f32x16& p0, f32x16& p1, const bf16* Ks, const bf16x8* qr, int r32, int hi, int colbase) {
;   p0 = f32x16{}; p1 = f32x16{};
;   __builtin_amdgcn_iglp_opt(1);
; #pragma unroll
;   for (int d0 = 0; d0 < ND0; ++d0) { int cb = (colbase + d0 * 16 + hi * 8) * 2;
;     bf16x8 b0 = *reinterpret_cast<const bf16x8*>((const char*)Ks + KSWZ(r32, cb));
;     bf16x8 b1 = *reinterpret_cast<const bf16x8*>((const char*)Ks + KSWZ(32 + r32, cb));
;     p0 = __builtin_amdgcn_mfma_f32_32x32x16_bf16(b0, qr[d0], p0, 0, 0, 0);
;     p1 = __builtin_amdgcn_mfma_f32_32x32x16_bf16(b1, qr[d0], p1, 0, 0, 0); }
; }
	ds_read_b128 v[0:3], v173 offset:32768
	ds_read_b128 v[32:35], v174 offset:32768
	ds_read_b128 v[4:7], v173 offset:40960
	ds_read_b128 v[36:39], v174 offset:40960
	s_waitcnt lgkmcnt(3)
	v_mfma_f32_32x32x16_bf16 v[16:31], v[0:3], v[126:129], 0
	s_waitcnt lgkmcnt(2)
	v_mfma_f32_32x32x16_bf16 v[16:31], v[32:35], v[122:125], v[16:31]
	v_or_b32_e32 v32, 64, v40
	v_xad_u32 v175, v32, v42, v41
	ds_read_b128 v[32:35], v175 offset:32768
	s_waitcnt lgkmcnt(2)
	v_mfma_f32_32x32x16_bf16 v[0:15], v[4:7], v[126:129], 0
	s_waitcnt lgkmcnt(1)
	v_mfma_f32_32x32x16_bf16 v[0:15], v[36:39], v[122:125], v[0:15]
	ds_read_b128 v[36:39], v175 offset:40960
	s_waitcnt lgkmcnt(1)
	v_mfma_f32_32x32x16_bf16 v[16:31], v[32:35], v[118:121], v[16:31]
	v_or_b32_e32 v32, 0x60, v40
	v_xad_u32 v177, v32, v42, v41
	ds_read_b128 v[32:35], v177 offset:32768
	s_waitcnt lgkmcnt(1)
	v_mfma_f32_32x32x16_bf16 v[0:15], v[36:39], v[118:121], v[0:15]
	ds_read_b128 v[36:39], v177 offset:40960
	s_waitcnt lgkmcnt(0)
	v_mfma_f32_32x32x16_bf16 v[0:15], v[36:39], v[114:117], v[0:15]
	v_add_u32_e32 v36, 0x60, v48
	v_mad_i64_i32 v[36:37], s[6:7], v36, s24, v[112:113]
	v_lshlrev_b64 v[44:45], 1, v[36:37]
	v_lshl_add_u64 v[36:37], s[18:19], 0, v[44:45]
	v_lshl_add_u64 v[44:45], s[16:17], 0, v[44:45]
	v_mfma_f32_32x32x16_bf16 v[16:31], v[32:35], v[114:117], v[16:31]
	global_load_dwordx4 v[44:47], v[44:45], off
	s_nop 10
	v_max_f32_e32 v32, v17, v17
	v_max_f32_e32 v33, v16, v16
	v_max_f32_e32 v32, v33, v32
	v_max3_f32 v32, v32, v18, v19
	v_max3_f32 v32, v32, v20, v21
	v_max3_f32 v32, v32, v22, v23
	v_max3_f32 v32, v32, v24, v25
	v_max3_f32 v32, v32, v26, v27
	v_max3_f32 v32, v32, v28, v29
	v_max3_f32 v32, v32, v30, v31
	v_max3_f32 v32, v32, v0, v1
	v_max3_f32 v32, v32, v2, v3
	v_max3_f32 v32, v32, v4, v5
	v_max3_f32 v32, v32, v6, v7
	v_max3_f32 v32, v32, v8, v9
	v_max3_f32 v32, v32, v10, v11
	v_max3_f32 v32, v32, v12, v13
	v_max3_f32 v32, v32, v14, v15
	v_mov_b32_e32 v33, v32
	s_nop 1
	v_permlane32_swap_b32_e32 v32, v33
	v_max_f32_e32 v33, v33, v33
	v_max_f32_e32 v32, v32, v32
	v_max_f32_e32 v49, v32, v33
	v_add_f32_e32 v32, 0x7149f2ca, v49
	v_cmp_ge_f32_e32 vcc, s78, v32
	v_add_u32_e32 v32, 64, v48
	v_mad_i64_i32 v[32:33], s[6:7], v32, s24, v[112:113]
	v_lshlrev_b64 v[40:41], 1, v[32:33]
	v_lshl_add_u64 v[32:33], s[18:19], 0, v[40:41]
	v_lshl_add_u64 v[40:41], s[16:17], 0, v[40:41]
	global_load_dwordx4 v[40:43], v[40:41], off
	s_cmp_eq_u64 vcc, exec
	global_load_dwordx4 v[36:39], v[36:37], off
	s_cselect_b64 vcc, -1, 0
	global_load_dwordx4 v[32:35], v[32:33], off
	s_cmpk_gt_i32 s8, 0xbf
	s_cselect_b64 s[6:7], -1, 0
	s_cmpk_lt_i32 s8, 0xc0
	s_cbranch_scc1 .LBB0_576
	v_add_u32_e32 v50, 0x80, v48
	v_mad_i64_i32 v[50:51], s[20:21], v50, s24, v[112:113]
	v_add_u32_e32 v54, 0xa0, v48
	v_lshlrev_b64 v[50:51], 1, v[50:51]
	v_mad_i64_i32 v[54:55], s[20:21], v54, s24, v[112:113]
	v_lshl_add_u64 v[52:53], s[18:19], 0, v[50:51]
	v_lshlrev_b64 v[54:55], 1, v[54:55]
	v_lshl_add_u64 v[50:51], s[16:17], 0, v[50:51]
	v_lshl_add_u64 v[56:57], s[18:19], 0, v[54:55]
	global_load_dwordx4 v[130:133], v[52:53], off
	global_load_dwordx4 v[134:137], v[56:57], off
	v_lshl_add_u64 v[52:53], s[16:17], 0, v[54:55]
	global_load_dwordx4 v[138:141], v[50:51], off
	global_load_dwordx4 v[142:145], v[52:53], off
